# COMB (merge of the three dilation groups): the six output-tile loads are issued before waiting on the three log-sum-exp loads (one memory round per token instead of two)
# baseline (speedup 1.0000x reference)
.LBB0_736:
	v_lshl_add_u64 v[12:13], v[8:9], 0, s[0:1]
	v_add_co_u32_e32 v14, vcc, 0x1a000000, v12
	v_lshl_add_u64 v[40:41], v[2:3], 0, s[0:1]
	s_nop 0
	v_addc_co_u32_e32 v15, vcc, 0, v13, vcc
	global_load_dword v0, v[14:15], off
	v_add_co_u32_e32 v14, vcc, 0x1a100000, v12
	v_lshl_add_u64 v[24:25], v[40:41], 0, s[36:37]
	s_nop 0
	v_addc_co_u32_e32 v15, vcc, 0, v13, vcc
	v_add_co_u32_e32 v12, vcc, 0x1a200000, v12
	global_load_dword v47, v[14:15], off
	s_nop 0
	v_addc_co_u32_e32 v13, vcc, 0, v13, vcc
	global_load_dword v48, v[12:13], off
	v_add_u32_e32 v10, s10, v10
	v_lshl_add_u64 v[2:3], v[2:3], 0, s[34:35]
	v_lshl_add_u64 v[8:9], v[8:9], 0, s[30:31]
	s_mov_b64 s[8:9], 0x14000000
	v_lshl_add_u64 v[16:17], v[40:41], 0, s[8:9]
	s_brev_b32 s8, 40
	v_add_co_u32_e32 v12, vcc, s8, v40
	s_mov_b32 s8, 0x16000000
	s_nop 0
	v_addc_co_u32_e32 v13, vcc, 0, v41, vcc
	v_add_co_u32_e32 v20, vcc, s8, v40
	s_mov_b64 s[8:9], 0x18000000
	s_nop 0
	v_addc_co_u32_e32 v21, vcc, 0, v41, vcc
	v_lshl_add_u64 v[32:33], v[40:41], 0, s[8:9]
	s_brev_b32 s8, 24
	global_load_dwordx4 v[12:15], v[12:13], off
	s_nop 0
	global_load_dwordx4 v[16:19], v[16:17], off offset:16
	s_nop 0
	global_load_dwordx4 v[20:23], v[20:21], off
	s_nop 0
	global_load_dwordx4 v[24:27], v[24:25], off offset:16
	v_add_co_u32_e32 v28, vcc, s8, v40
	s_nop 0
	v_addc_co_u32_e32 v29, vcc, 0, v41, vcc
	global_load_dwordx4 v[28:31], v[28:29], off
	s_nop 0
	global_load_dwordx4 v[32:35], v[32:33], off offset:16
	s_waitcnt vmcnt(6)
	v_max3_f32 v49, v0, v47, v48
	v_sub_f32_e32 v0, v0, v49
	v_mul_f32_e32 v0, 0x3fb8aa3b, v0
	v_exp_f32_e32 v37, v0
	v_sub_f32_e32 v0, v47, v49
	v_mul_f32_e32 v0, 0x3fb8aa3b, v0
	v_sub_f32_e32 v47, v48, v49
	v_exp_f32_e32 v0, v0
	v_mul_f32_e32 v47, 0x3fb8aa3b, v47
	v_exp_f32_e32 v36, v47
	v_add_f32_e32 v47, v37, v0
	v_add_f32_e32 v47, v36, v47
	v_div_scale_f32 v48, s[100:101], v47, v47, 1.0
	v_rcp_f32_e32 v49, v48
	s_nop 0
	v_fma_f32 v50, -v48, v49, 1.0
	v_fmac_f32_e32 v49, v50, v49
	v_div_scale_f32 v50, vcc, 1.0, v47, 1.0
	v_mul_f32_e32 v51, v50, v49
	v_fma_f32 v52, -v48, v51, v50
	v_fmac_f32_e32 v51, v52, v49
	v_fma_f32 v48, -v48, v51, v50
	v_div_fmas_f32 v48, v48, v49, v51
	v_div_fixup_f32 v38, v48, v47, 1.0
	v_mul_f32_e32 v0, v0, v38
	v_pk_mul_f32 v[36:37], v[36:37], v[38:39] op_sel_hi:[1,0]
	s_waitcnt vmcnt(5)
	v_lshlrev_b32_e32 v38, 16, v12
	s_waitcnt vmcnt(3)
	v_lshlrev_b32_e32 v42, 16, v20
	v_and_b32_e32 v43, 0xffff0000, v20
	v_lshlrev_b32_e32 v20, 16, v21
	v_and_b32_e32 v21, 0xffff0000, v21
	v_and_b32_e32 v39, 0xffff0000, v12
	v_lshlrev_b32_e32 v12, 16, v13
	v_and_b32_e32 v13, 0xffff0000, v13
	v_pk_mul_f32 v[20:21], v[0:1], v[20:21] op_sel_hi:[0,1]
	s_waitcnt vmcnt(1)
	v_lshlrev_b32_e32 v44, 16, v28
	v_and_b32_e32 v45, 0xffff0000, v28
	v_lshlrev_b32_e32 v28, 16, v29
	v_and_b32_e32 v29, 0xffff0000, v29
	v_pk_fma_f32 v[12:13], v[36:37], v[12:13], v[20:21] op_sel:[1,0,0]
	v_pk_mul_f32 v[42:43], v[0:1], v[42:43] op_sel_hi:[0,1]
	v_pk_fma_f32 v[20:21], v[36:37], v[28:29], v[12:13] op_sel_hi:[0,1,1]
	v_lshlrev_b32_e32 v28, 16, v22
	v_and_b32_e32 v29, 0xffff0000, v22
	v_lshlrev_b32_e32 v12, 16, v14
	v_and_b32_e32 v13, 0xffff0000, v14
	v_pk_mul_f32 v[28:29], v[0:1], v[28:29] op_sel_hi:[0,1]
	v_pk_fma_f32 v[38:39], v[36:37], v[38:39], v[42:43] op_sel:[1,0,0]
	v_lshlrev_b32_e32 v42, 16, v30
	v_and_b32_e32 v43, 0xffff0000, v30
	v_pk_fma_f32 v[12:13], v[36:37], v[12:13], v[28:29] op_sel:[1,0,0]
	v_lshlrev_b32_e32 v14, 16, v23
	v_pk_fma_f32 v[28:29], v[36:37], v[42:43], v[12:13] op_sel_hi:[0,1,1]
	v_lshlrev_b32_e32 v12, 16, v15
	v_and_b32_e32 v13, 0xffff0000, v15
	v_and_b32_e32 v15, 0xffff0000, v23
	v_lshlrev_b32_e32 v22, 16, v31
	v_and_b32_e32 v23, 0xffff0000, v31
	v_pk_mul_f32 v[14:15], v[0:1], v[14:15] op_sel_hi:[0,1]
	v_lshlrev_b32_e32 v30, 16, v24
	v_and_b32_e32 v31, 0xffff0000, v24
	v_pk_fma_f32 v[12:13], v[36:37], v[12:13], v[14:15] op_sel:[1,0,0]
	v_lshlrev_b32_e32 v14, 16, v16
	v_and_b32_e32 v15, 0xffff0000, v16
	v_pk_mul_f32 v[30:31], v[0:1], v[30:31] op_sel_hi:[0,1]
	s_waitcnt vmcnt(0)
	v_lshlrev_b32_e32 v42, 16, v32
	v_and_b32_e32 v43, 0xffff0000, v32
	v_pk_fma_f32 v[14:15], v[36:37], v[14:15], v[30:31] op_sel:[1,0,0]
	v_lshlrev_b32_e32 v16, 16, v25
	v_pk_fma_f32 v[30:31], v[36:37], v[42:43], v[14:15] op_sel_hi:[0,1,1]
	v_lshlrev_b32_e32 v14, 16, v17
	v_and_b32_e32 v15, 0xffff0000, v17
	v_and_b32_e32 v17, 0xffff0000, v25
	v_pk_mul_f32 v[16:17], v[0:1], v[16:17] op_sel_hi:[0,1]
	v_lshlrev_b32_e32 v24, 16, v33
	v_and_b32_e32 v25, 0xffff0000, v33
	v_pk_fma_f32 v[14:15], v[36:37], v[14:15], v[16:17] op_sel:[1,0,0]
	v_lshlrev_b32_e32 v16, 16, v26
	v_and_b32_e32 v17, 0xffff0000, v26
	v_pk_fma_f32 v[22:23], v[36:37], v[22:23], v[12:13] op_sel_hi:[0,1,1]
	v_and_b32_e32 v13, 0xffff0000, v19
	v_and_b32_e32 v12, 0xffff0000, v35
	v_pk_fma_f32 v[24:25], v[36:37], v[24:25], v[14:15] op_sel_hi:[0,1,1]
	v_lshlrev_b32_e32 v14, 16, v18
	v_and_b32_e32 v15, 0xffff0000, v18
	v_pk_mul_f32 v[16:17], v[0:1], v[16:17] op_sel_hi:[0,1]
	v_lshlrev_b32_e32 v11, 16, v19
	v_lshlrev_b32_e32 v18, 16, v34
	v_and_b32_e32 v19, 0xffff0000, v34
	v_pk_fma_f32 v[14:15], v[36:37], v[14:15], v[16:17] op_sel:[1,0,0]
	v_pk_mul_f32 v[12:13], v[36:37], v[12:13]
	v_pk_fma_f32 v[18:19], v[36:37], v[18:19], v[14:15] op_sel_hi:[0,1,1]
	v_mov_b32_e32 v15, v13
	v_cvt_pk_bf16_f32 v13, v20, v21
	v_add_co_u32_e32 v20, vcc, 0x27000000, v40
	v_lshlrev_b32_e32 v46, 16, v35
	v_mul_f32_e32 v14, v37, v11
	v_lshlrev_b32_e32 v26, 16, v27
	v_and_b32_e32 v27, 0xffff0000, v27
	v_addc_co_u32_e32 v21, vcc, 0, v41, vcc
	v_pk_fma_f32 v[38:39], v[36:37], v[44:45], v[38:39] op_sel_hi:[0,1,1]
	v_mul_f32_e32 v16, v36, v46
	v_pk_fma_f32 v[14:15], v[0:1], v[26:27], v[14:15] op_sel_hi:[0,1,1]
	v_mov_b32_e32 v17, v12
	v_cmp_lt_i32_e32 vcc, s11, v10
	v_pk_add_f32 v[26:27], v[16:17], v[14:15]
	v_cvt_pk_bf16_f32 v12, v38, v39
	v_cvt_pk_bf16_f32 v14, v28, v29
	v_cvt_pk_bf16_f32 v15, v22, v23
	s_or_b64 s[6:7], vcc, s[6:7]
	v_cvt_pk_bf16_f32 v16, v30, v31
	v_cvt_pk_bf16_f32 v17, v24, v25
	v_cvt_pk_bf16_f32 v18, v18, v19
	v_cvt_pk_bf16_f32 v19, v26, v27
	global_store_dwordx4 v[20:21], v[12:15], off
	global_store_dwordx4 v[20:21], v[16:19], off offset:16
	s_andn2_b64 exec, exec, s[6:7]
	s_cbranch_execnz .LBB0_736
